# code placement: 4-byte pad after the merge GEMM so the later phases keep the byte phase of the previous best
# baseline (speedup 1.0000x reference)
; #define PG8_WAIT_V(n) asm volatile("s_waitcnt vmcnt(" #n ")" ::: "memory")
; #define PG8_BAR __builtin_amdgcn_s_barrier()
; template <class Epi, class Sched, bool ALIGN_EPI = false, bool SP2 = false>
; __device__ __forceinline__ void gemm_phase(PG8_LAS unsigned char* lds, const Gemm g, const Sched& S, const Epi& E) {
;     ...
;     PG8_WAIT_V(0);
;     if constexpr (!ALIGN_EPI) { if (wr == 0) PG8_BAR; }
;     PG8_BAR;
.LBB0_1301:
	s_nop 0
	s_waitcnt vmcnt(0)
	v_mov_b32_e32 v238, v237
	v_mov_b32_e32 v237, v239
	v_mov_b32_e32 v240, v194
	v_mov_b32_e32 v194, v242
	v_bfrev_b32_e32 v241, 0.5
	v_mov_b32_e32 v242, 0x2200
	s_barrier
